# P3: first two GS-tile loads issued in the unit set-up block; P3 zeroing-block vmcnt waits removed
# baseline (speedup 1.0000x reference)
.LBB0_593:
	v_writelane_b32 v254, s3, 27
	s_lshl_b32 s1, s3, 20
	v_writelane_b32 v254, s1, 29
	s_and_b64 s[2:3], s[10:11], exec
	v_writelane_b32 v254, s6, 25
	s_cselect_b32 vcc_lo, s1, s96
	s_lshl_b32 s1, s6, 20
	v_writelane_b32 v254, s10, 23
	s_and_b64 s[2:3], s[10:11], exec
	s_cselect_b32 vcc_hi, s1, s38
	v_writelane_b32 v254, s11, 24
	v_writelane_b32 v254, s1, 31
	s_lshl_b32 s1, s0, 20
	s_lshl_b32 s0, s92, 17
	s_add_i32 s91, s1, s0
	v_writelane_b32 v254, s1, 33
	s_or_b32 s90, s91, 0x10000
	v_readlane_b32 s100, v252, 45
	v_readlane_b32 s32, v252, 46
	s_add_u32 s98, s100, s91
	s_addc_u32 s99, s32, 0
	v_lshl_add_u64 v[92:93], s[98:99], 0, v[220:221]
	global_load_dwordx4 v[84:87], v[92:93], off
	s_add_u32 s98, s100, s90
	s_addc_u32 s99, s32, 0
	v_lshl_add_u64 v[92:93], s[98:99], 0, v[220:221]
	global_load_dwordx4 v[88:91], v[92:93], off
	s_or_b32 s88, s91, 0x2000
	s_or_b32 s81, s91, 0x12000
	s_or_b32 s80, s91, 0x4000
	s_or_b32 s89, s91, 0x14000
	s_or_b32 s33, s91, 0x6000
	s_or_b32 s3, s91, 0x16000
	s_or_b32 s2, s91, 0x8000
	s_or_b32 s1, s91, 0x18000
	s_or_b32 s0, s91, 0xa000
	s_or_b32 s37, s91, 0x1a000
	s_or_b32 s52, s91, 0xc000
	s_or_b32 s56, s91, 0x1c000
	s_or_b32 s39, s91, 0xe000
	s_or_b32 s36, s91, 0x1e000
	v_readlane_b32 s70, v251, 1
	v_readlane_b32 s71, v251, 2
	s_add_u32 s4, s70, s91
	s_addc_u32 s5, s71, 0
	s_add_u32 s6, s70, s90
	s_addc_u32 s7, s71, 0
	s_add_u32 s8, s70, s88
	s_addc_u32 s9, s71, 0
	s_add_u32 s10, s70, s81
	s_addc_u32 s11, s71, 0
	s_add_u32 s12, s70, s80
	s_addc_u32 s13, s71, 0
	s_add_u32 s14, s70, s89
	s_addc_u32 s15, s71, 0
	s_add_u32 s16, s70, s33
	s_addc_u32 s17, s71, 0
	s_add_u32 s18, s70, s3
	s_addc_u32 s19, s71, 0
	s_add_u32 s28, s70, s2
	s_addc_u32 s29, s71, 0
	s_add_u32 s40, s70, s1
	s_addc_u32 s41, s71, 0
	s_add_u32 s42, s70, s0
	s_addc_u32 s43, s71, 0
	s_add_u32 s44, s70, s37
	s_addc_u32 s45, s71, 0
	v_writelane_b32 v254, s52, 41
	s_add_u32 s52, s70, s52
	s_addc_u32 s53, s71, 0
	v_writelane_b32 v254, s56, 39
	s_add_u32 s56, s70, s56
	s_addc_u32 s57, s71, 0
	s_add_u32 s68, s70, s39
	s_addc_u32 s69, s71, 0
	v_mov_b32_e32 v80, v81
	v_mov_b32_e32 v82, v81
	v_mov_b32_e32 v83, v81
	v_writelane_b32 v254, s39, 37
	s_add_u32 s70, s70, s36
	v_mov_b64_e32 v[0:1], v[80:81]
	v_mov_b64_e32 v[4:5], v[80:81]
	v_mov_b64_e32 v[16:17], v[80:81]
	v_mov_b64_e32 v[20:21], v[80:81]
	v_mov_b64_e32 v[32:33], v[80:81]
	v_mov_b64_e32 v[36:37], v[80:81]
	v_mov_b64_e32 v[48:49], v[80:81]
	v_mov_b64_e32 v[52:53], v[80:81]
	v_mov_b64_e32 v[8:9], v[80:81]
	v_mov_b64_e32 v[12:13], v[80:81]
	v_mov_b64_e32 v[24:25], v[80:81]
	v_mov_b64_e32 v[28:29], v[80:81]
	v_mov_b64_e32 v[40:41], v[80:81]
	v_mov_b64_e32 v[44:45], v[80:81]
	v_mov_b64_e32 v[56:57], v[80:81]
	v_mov_b64_e32 v[60:61], v[80:81]
	v_mov_b64_e32 v[64:65], v[80:81]
	v_mov_b64_e32 v[68:69], v[80:81]
	v_mov_b64_e32 v[106:107], v[82:83]
	v_mov_b64_e32 v[110:111], v[82:83]
	v_mov_b64_e32 v[122:123], v[82:83]
	v_mov_b64_e32 v[126:127], v[82:83]
	v_mov_b64_e32 v[138:139], v[82:83]
	v_mov_b64_e32 v[142:143], v[82:83]
	v_mov_b64_e32 v[72:73], v[80:81]
	v_mov_b64_e32 v[76:77], v[80:81]
	v_mov_b64_e32 v[114:115], v[82:83]
	v_mov_b64_e32 v[118:119], v[82:83]
	v_mov_b64_e32 v[130:131], v[82:83]
	v_mov_b64_e32 v[134:135], v[82:83]
	v_mov_b64_e32 v[146:147], v[82:83]
	v_mov_b64_e32 v[150:151], v[82:83]
	v_writelane_b32 v254, s36, 35
	s_addc_u32 s71, s71, 0
	s_add_i32 s93, s38, 0x8000
	s_mov_b32 s38, -2
	s_mov_b32 s39, 0
	v_mov_b64_e32 v[2:3], v[82:83]
	v_mov_b64_e32 v[6:7], v[82:83]
	v_mov_b64_e32 v[18:19], v[82:83]
	v_mov_b64_e32 v[22:23], v[82:83]
	v_mov_b64_e32 v[34:35], v[82:83]
	v_mov_b64_e32 v[38:39], v[82:83]
	v_mov_b64_e32 v[50:51], v[82:83]
	v_mov_b64_e32 v[54:55], v[82:83]
	v_mov_b64_e32 v[10:11], v[82:83]
	v_mov_b64_e32 v[14:15], v[82:83]
	v_mov_b64_e32 v[26:27], v[82:83]
	v_mov_b64_e32 v[30:31], v[82:83]
	v_mov_b64_e32 v[42:43], v[82:83]
	v_mov_b64_e32 v[46:47], v[82:83]
	v_mov_b64_e32 v[58:59], v[82:83]
	v_mov_b64_e32 v[62:63], v[82:83]
	v_mov_b64_e32 v[66:67], v[82:83]
	v_mov_b64_e32 v[70:71], v[82:83]
	v_mov_b64_e32 v[104:105], v[80:81]
	v_mov_b64_e32 v[108:109], v[80:81]
	v_mov_b64_e32 v[120:121], v[80:81]
	v_mov_b64_e32 v[124:125], v[80:81]
	v_mov_b64_e32 v[136:137], v[80:81]
	v_mov_b64_e32 v[140:141], v[80:81]
	v_mov_b64_e32 v[74:75], v[82:83]
	v_mov_b64_e32 v[78:79], v[82:83]
	v_mov_b64_e32 v[112:113], v[80:81]
	v_mov_b64_e32 v[116:117], v[80:81]
	v_mov_b64_e32 v[128:129], v[80:81]
	v_mov_b64_e32 v[132:133], v[80:81]
	v_mov_b64_e32 v[144:145], v[80:81]
	v_mov_b64_e32 v[148:149], v[80:81]
	s_branch .LBB0_595

.LBB0_599:
	v_readlane_b32 s8, v252, 45
	s_add_u32 s4, s8, s91
	v_readlane_b32 s9, v252, 46
	s_addc_u32 s5, s9, 0
	s_nop 0
	v_lshl_add_u64 v[82:83], s[4:5], 0, v[220:221]
	v_mov_b32_e32 v228, v84
	v_mov_b32_e32 v229, v85
	v_mov_b32_e32 v230, v86
	v_mov_b32_e32 v231, v87
	s_add_u32 s4, s8, s90
	s_addc_u32 s5, s9, 0
	s_add_u32 s6, s8, s88
	v_lshl_add_u64 v[82:83], s[4:5], 0, v[220:221]
	v_mov_b32_e32 v240, v88
	v_mov_b32_e32 v241, v89
	v_mov_b32_e32 v242, v90
	v_mov_b32_e32 v243, v91
	s_addc_u32 s7, s9, 0
	s_add_u32 s4, s8, s81
	v_lshl_add_u64 v[82:83], s[6:7], 0, v[220:221]
	global_load_dwordx4 v[204:207], v[82:83], off
	s_addc_u32 s5, s9, 0
	s_add_u32 s6, s8, s80
	v_lshl_add_u64 v[82:83], s[4:5], 0, v[220:221]
	global_load_dwordx4 v[200:203], v[82:83], off
	s_addc_u32 s7, s9, 0
	s_add_u32 s4, s8, s89
	v_lshl_add_u64 v[82:83], s[6:7], 0, v[220:221]
	global_load_dwordx4 v[196:199], v[82:83], off
	s_addc_u32 s5, s9, 0
	s_add_u32 s6, s8, s33
	v_lshl_add_u64 v[82:83], s[4:5], 0, v[220:221]
	global_load_dwordx4 v[192:195], v[82:83], off
	s_addc_u32 s7, s9, 0
	s_add_u32 s4, s8, s3
	v_lshl_add_u64 v[82:83], s[6:7], 0, v[220:221]
	global_load_dwordx4 v[188:191], v[82:83], off
	s_addc_u32 s5, s9, 0
	s_add_u32 s2, s8, s2
	v_lshl_add_u64 v[82:83], s[4:5], 0, v[220:221]
	global_load_dwordx4 v[184:187], v[82:83], off
	s_addc_u32 s3, s9, 0
	s_add_u32 s4, s8, s1
	v_lshl_add_u64 v[82:83], s[2:3], 0, v[220:221]
	global_load_dwordx4 v[180:183], v[82:83], off
	s_addc_u32 s5, s9, 0
	s_add_u32 s0, s8, s0
	v_lshl_add_u64 v[82:83], s[4:5], 0, v[220:221]
	global_load_dwordx4 v[176:179], v[82:83], off
	s_addc_u32 s1, s9, 0
	s_add_u32 s2, s8, s37
	v_lshl_add_u64 v[82:83], s[0:1], 0, v[220:221]
	global_load_dwordx4 v[172:175], v[82:83], off
	s_addc_u32 s3, s9, 0
	v_readlane_b32 s0, v254, 41
	v_lshl_add_u64 v[82:83], s[2:3], 0, v[220:221]
	global_load_dwordx4 v[168:171], v[82:83], off
	s_add_u32 s0, s8, s0
	s_addc_u32 s1, s9, 0
	v_readlane_b32 s2, v254, 39
	v_lshl_add_u64 v[82:83], s[0:1], 0, v[220:221]
	global_load_dwordx4 v[164:167], v[82:83], off
	s_add_u32 s2, s8, s2
	s_addc_u32 s3, s9, 0
	v_readlane_b32 s0, v254, 37
	v_lshl_add_u64 v[82:83], s[2:3], 0, v[220:221]
	global_load_dwordx4 v[160:163], v[82:83], off
	s_add_u32 s0, s8, s0
	s_addc_u32 s1, s9, 0
	v_readlane_b32 s2, v254, 35
	v_lshl_add_u64 v[82:83], s[0:1], 0, v[220:221]
	global_load_dwordx4 v[156:159], v[82:83], off
	s_add_u32 s2, s8, s2
	s_addc_u32 s3, s9, 0
	s_lshl_b32 s0, s92, 16
	v_lshl_add_u64 v[82:83], s[2:3], 0, v[220:221]
	global_load_dwordx4 v[152:155], v[82:83], off
	v_readlane_b32 s1, v254, 33
	s_add_i32 s0, s1, s0
	v_readlane_b32 s8, v254, 10
	v_readlane_b32 s98, v254, 43
	v_readlane_b32 s99, v254, 44
	s_and_b64 vcc, exec, s[98:99]
	s_cbranch_vccz .Lab_p3
	s_barrier
